# scan loader: hand-written loop + L2 touch prefetch of step n+5 operands (one global_load_dword per loader wave per step)
# baseline (speedup 1.0000x reference)
; #define LAS __attribute__((address_space(3)))
; #define SCAN_BAR() do { asm volatile("" ::: "memory"); __builtin_amdgcn_s_barrier(); asm volatile("" ::: "memory"); } while (0)
; #define SCAN_ISSUE(n, slot) do { const unsigned char* s_ = src + (size_t)(n) * step_stride; LAS unsigned char* d_ = lds + (slot) * SR_SLOT + p0 * 1024; \
;         _Pragma("unroll") for (int i_ = 0; i_ < 7; ++i_) glds16_asm(s_ + i_ * 1024, d_ + i_ * 1024, true  ); \
;         if (lw < 2) glds16_asm(s_ + 7 * 1024, d_ + 7 * 1024, true); } while (0)
; #define SCAN_ZISSUE(n) do { const unsigned char* z_ = zsrc + (size_t)(n) * 64 * 2048; LAS unsigned char* d_ = lds + ZT_OFF + ((n) & 1) * 8192 + (2 * lw) * 1024; \
;         glds16_asm(z_, d_, false); glds16_asm(z_ + 8 * 2048, d_ + 1024, false); } while (0)
; __device__ __forceinline__ void scan_prompt_wg(const Params& P, LAS unsigned char* lds, int s, int h, int wave, int lane) {
;     constexpr int NST = 128;
;     const unsigned char* ops0 = P.ws + WS_OPS + ((size_t)(s * 128) * 8 + h) * OPS_UNIT;
;     const size_t step_stride = (size_t)8 * OPS_UNIT;
;     ...
;     if (wave >= 4) {
;         const int lw = wave - 4;
;         const int np = (lw < 2) ? 8 : 7, p0 = (lw < 2) ? 8 * lw : 16 + 7 * (lw - 2);
;         const unsigned char* src = ops0 + (size_t)p0 * 1024 + lane * 16;
;     ...
;         const int ftid = lw * 64 + lane, ft = ftid >> 2, fp = ftid & 3;
;         float gg[16];
; #pragma unroll
;         for (int i = 0; i < 16; ++i) gg[i] = P.gdn_g[16 * fp + i];
;         bf16* Mr = (bf16*)(P.ws + WS_MIX) + ((size_t)s * TP + ft) * 1024 + h * 64 + 16 * fp;
;         const unsigned char* zsrc = (const unsigned char*)((const bf16*)(P.ws + WS_Z) + ((size_t)s * TP + 16 * lw + (lane >> 3)) * 1024 + h * 64) + (lane & 7) * 16;
;     ...
; #pragma unroll
;         for (int i = 0; i < 16; ++i) asm volatile("" : "+v"(gg[i]));
;         SCAN_ZISSUE(0);
;         SCAN_ISSUE(0, 0); SCAN_ISSUE(1, 1); SCAN_ISSUE(2, 2);
;         if (lw < 2) asm volatile("s_waitcnt vmcnt(16)" ::: "memory"); else asm volatile("s_waitcnt vmcnt(14)" ::: "memory");
;         SCAN_BAR();
.LBB0_663:
	v_lshl_or_b32 v15, s17, 6, v164
	s_lshl_b32 s10, s18, 1
	v_lshrrev_b32_e32 v26, 2, v15
	v_mov_b32_e32 v27, 0
	s_add_u32 s4, s4, s10
	v_lshl_add_u64 v[30:31], s[14:15], 0, v[26:27]
	s_addc_u32 s5, s5, 0
	v_lshlrev_b64 v[30:31], 11, v[30:31]
	v_lshl_add_u64 v[30:31], s[4:5], 0, v[30:31]
	v_mov_b32_e32 v15, v27
	v_lshlrev_b32_e32 v23, 7, v26
	v_lshlrev_b32_e32 v27, 5, v28
	s_add_i32 s4, 0, 0x22200
	v_add3_u32 v26, 0, v23, v27
	v_add3_u32 v27, s4, v23, v27
	s_add_u32 s4, s27, s28
	s_addc_u32 s5, s26, 0
	s_add_u32 s4, s4, s12
	s_addc_u32 s5, s5, s13
	v_readlane_b32 s12, v247, 0
	v_readlane_b32 s13, v247, 1
	s_add_u32 s4, s12, s4
	s_addc_u32 s5, s13, s5
	v_lshl_add_u64 v[18:19], s[4:5], 0, v[18:19]
	s_mov_b64 s[4:5], 0x23900000
	v_lshl_add_u64 v[18:19], v[18:19], 0, s[4:5]
	s_add_u32 s4, s16, s14
	s_addc_u32 s5, s15, 0
	v_lshl_add_u64 v[24:25], s[4:5], 0, v[24:25]
	v_lshlrev_b64 v[24:25], 11, v[24:25]
	v_lshl_or_b32 v23, s2, 7, v24
	s_barrier
	v_or_b32_e32 v24, v23, v22
	v_lshlrev_b32_e32 v14, 1, v14
	v_lshl_add_u64 v[22:23], s[12:13], 0, v[24:25]
	s_mov_b64 s[4:5], 0x3620000
	s_mov_b32 s11, 0
	v_lshl_add_u64 v[14:15], v[30:31], 0, v[14:15]
	v_lshl_add_u64 v[22:23], v[22:23], 0, s[4:5]
	s_mov_b32 s2, 3
	s_movk_i32 s43, 0x2000
	s_mov_b32 s10, -1
	s_mov_b32 s44, 0x1e000
	v_mov_b32_e32 v24, 0x358637bd
	s_mov_b64 s[4:5], 0x4000
	s_mov_b64 s[12:13], 0xf0000
	s_mov_b64 s[14:15], 0xf0400
	s_mov_b64 s[16:17], 0xf0800
	s_mov_b64 s[18:19], 0xf0c00
	s_mov_b64 s[24:25], 0xf1000
	s_mov_b64 s[26:27], 0xf1400
	s_mov_b64 s[28:29], 0xf1800
	s_mov_b64 s[30:31], 0xf1c00
	s_mov_b64 s[34:35], 0x50000
	s_mov_b64 s[36:37], 0x20000
	v_mul_u32_u24_e32 v104, 0x70, v164
	v_add_u32_e32 v104, 0x190000, v104
	v_mov_b32_e32 v105, 0
	s_branch .LBB0_666

; #define SCAN_ISSUE(n, slot) do { const unsigned char* s_ = src + (size_t)(n) * step_stride; LAS unsigned char* d_ = lds + (slot) * SR_SLOT + p0 * 1024; \
;         _Pragma("unroll") for (int i_ = 0; i_ < 7; ++i_) glds16_asm(s_ + i_ * 1024, d_ + i_ * 1024, true  ); \
;         if (lw < 2) glds16_asm(s_ + 7 * 1024, d_ + 7 * 1024, true); } while (0)
; #define SCAN_ZISSUE(n) do { const unsigned char* z_ = zsrc + (size_t)(n) * 64 * 2048; LAS unsigned char* d_ = lds + ZT_OFF + ((n) & 1) * 8192 + (2 * lw) * 1024; \
;         glds16_asm(z_, d_, false); glds16_asm(z_ + 8 * 2048, d_ + 1024, false); } while (0)
; __device__ __forceinline__ void scan_prompt_wg(const Params& P, LAS unsigned char* lds, int s, int h, int wave, int lane) {
;     ...
;             if (n < NST) {
;                 asm volatile("s_waitcnt lgkmcnt(0)" ::: "memory");
;                 if (n + 1 < NST) SCAN_ZISSUE(n + 1);
;                 if (n + 3 < NST) SCAN_ISSUE(n + 3, slot);
;                 if (n >= 2 && n + 3 < NST) { if (lw < 2) asm volatile("s_waitcnt vmcnt(20)" ::: "memory"); else asm volatile("s_waitcnt vmcnt(18)" ::: "memory"); }
;                 else asm volatile("s_waitcnt vmcnt(0)" ::: "memory");
.Lld_noz:
	s_cmpk_gt_u32 s45, 0x7c
	s_cbranch_scc1 .Lld_noops
	s_mul_i32 s20, s2, 0x7800
	s_add_i32 s38, s42, s20
	v_lshl_add_u64 v[100:101], v[18:19], 0, s[12:13]
	s_mov_b32 m0, s38
	s_nop 0
	global_load_lds_dwordx4 v[100:101], off
	v_lshl_add_u64 v[102:103], v[18:19], 0, s[14:15]
	s_add_i32 s20, s38, 0x400
	s_mov_b32 m0, s20
	s_nop 0
	global_load_lds_dwordx4 v[102:103], off
	v_lshl_add_u64 v[100:101], v[18:19], 0, s[16:17]
	s_add_i32 s20, s38, 0x800
	s_mov_b32 m0, s20
	s_nop 0
	global_load_lds_dwordx4 v[100:101], off
	v_lshl_add_u64 v[102:103], v[18:19], 0, s[18:19]
	s_add_i32 s20, s38, 0xc00
	s_mov_b32 m0, s20
	s_nop 0
	global_load_lds_dwordx4 v[102:103], off
	v_lshl_add_u64 v[100:101], v[18:19], 0, s[24:25]
	s_add_i32 s20, s38, 0x1000
	s_mov_b32 m0, s20
	s_nop 0
	global_load_lds_dwordx4 v[100:101], off
	v_lshl_add_u64 v[102:103], v[18:19], 0, s[26:27]
	s_add_i32 s20, s38, 0x1400
	s_mov_b32 m0, s20
	s_nop 0
	global_load_lds_dwordx4 v[102:103], off
	v_lshl_add_u64 v[100:101], v[18:19], 0, s[28:29]
	s_add_i32 s20, s38, 0x1800
	s_mov_b32 m0, s20
	s_nop 0
	global_load_lds_dwordx4 v[100:101], off
	s_and_b64 vcc, exec, s[8:9]
	s_cbranch_vccnz .Lld_noops
	v_lshl_add_u64 v[102:103], v[18:19], 0, s[30:31]
	s_add_i32 s20, s38, 0x1c00
	s_mov_b32 m0, s20
	s_nop 0
	global_load_lds_dwordx4 v[102:103], off
.Lld_noops:
	s_mov_b32 m0, s39
	s_cmp_lt_u32 s45, 2
	s_cbranch_scc1 .Lld_notouch
	s_cmpk_gt_u32 s45, 0x7a
	s_cbranch_scc1 .Lld_notouch
	v_lshl_add_u64 v[106:107], v[18:19], 0, v[104:105]
	global_load_dword v110, v[106:107], off
; #define LAS __attribute__((address_space(3)))
; __device__ __forceinline__ unsigned pk2(float lo, float hi) { return pg8::cvt_pk_bf16_v(lo, hi); }
; __device__ __forceinline__ float siluf(float x) { return x * __builtin_amdgcn_rcpf(1.0f + __expf(-x)); }
; __device__ __forceinline__ void scan_prompt_wg(const Params& P, LAS unsigned char* lds, int s, int h, int wave, int lane) {
;     ...
;             if (n >= 1) {
;                 const LAS unsigned char* ot = lds + (((n - 1) & 1) ? OT_B : OT_A) + ft * 128 + fp * 32;
;                 const LAS unsigned char* zt = lds + ZT_OFF + ((n - 1) & 1) * 8192 + ft * 128 + fp * 32;
;                 float o[16], zf[16]; { float t0[8], t1[8]; unpack8(*(const LAS v4u*)ot, t0); unpack8(*(const LAS v4u*)(ot + 16), t1);
; #pragma unroll
;                     for (int i = 0; i < 8; ++i) { o[i] = t0[i]; o[8 + i] = t1[i]; }
;                     unpack8(*(const LAS v4u*)zt, t0); unpack8(*(const LAS v4u*)(zt + 16), t1);
; #pragma unroll
;                     for (int i = 0; i < 8; ++i) { zf[i] = t0[i]; zf[8 + i] = t1[i]; } }
;                 float ss = 0.f;
; #pragma unroll
;                 for (int i = 0; i < 16; ++i) ss += o[i] * o[i];
;                 ss += __shfl_xor(ss, 1); ss += __shfl_xor(ss, 2);
;                 const float rstd = __builtin_amdgcn_rsqf(ss * (1.0f / 64.0f) + 1e-6f);
;                 float r[16];
; #pragma unroll
;                 for (int i = 0; i < 16; ++i) r[i] = o[i] * rstd * gg[i] * siluf(zf[i]);
;                 bf16* mp = Mr + (size_t)(n - 1) * 64 * 1024;
;                 v4u w0, w1; w0.x = pk2(r[0], r[1]); w0.y = pk2(r[2], r[3]); w0.z = pk2(r[4], r[5]); w0.w = pk2(r[6], r[7]); w1.x = pk2(r[8], r[9]); w1.y = pk2(r[10], r[11]); w1.z = pk2(r[12], r[13]); w1.w = pk2(r[14], r[15]);
;                 *(v4u*)mp = w0; *(v4u*)(mp + 8) = w1;
;             }
;             if (n < NST) {
;                 asm volatile("s_waitcnt lgkmcnt(0)" ::: "memory");
;                 if (n + 1 < NST) SCAN_ZISSUE(n + 1);
;                 if (n + 3 < NST) SCAN_ISSUE(n + 3, slot);
;                 if (n >= 2 && n + 3 < NST) { if (lw < 2) asm volatile("s_waitcnt vmcnt(20)" ::: "memory"); else asm volatile("s_waitcnt vmcnt(18)" ::: "memory"); }
;                 else asm volatile("s_waitcnt vmcnt(0)" ::: "memory");
;                 slot = (slot == SR_NS - 1) ? 0 : slot + 1;
;                 SCAN_BAR();
.Lld_notouch:
	s_cmp_eq_u32 s45, 0
	s_cbranch_scc1 .Lld_wait
	v_lshlrev_b32_e32 v34, 16, v31
	v_mul_f32_e32 v33, 0xbfb8aa3b, v34
	v_exp_f32_e32 v48, v33
	v_lshlrev_b32_e32 v62, 16, v29
	s_waitcnt lgkmcnt(2)
	v_lshlrev_b32_e32 v49, 16, v38
	v_add_f32_e32 v25, 1.0, v48
	v_rcp_f32_e32 v25, v25
	v_and_b32_e32 v48, 0xffff0000, v38
	v_and_b32_e32 v63, 0xffff0000, v29
	v_mul_f32_e32 v29, 0xbfb8aa3b, v63
	v_mul_f32_e32 v38, v25, v34
	v_mul_f32_e32 v25, 0xbfb8aa3b, v62
	v_exp_f32_e32 v25, v25
	v_exp_f32_e32 v29, v29
	v_lshlrev_b32_e32 v68, 16, v37
	v_and_b32_e32 v69, 0xffff0000, v37
	v_add_f32_e32 v25, 1.0, v25
	v_rcp_f32_e32 v66, v25
	v_add_f32_e32 v25, 1.0, v29
	v_rcp_f32_e32 v67, v25
	v_and_b32_e32 v37, 0xffff0000, v28
	v_and_b32_e32 v60, 0xffff0000, v31
	s_waitcnt lgkmcnt(1)
	v_lshlrev_b32_e32 v74, 16, v43
	v_pk_mul_f32 v[62:63], v[66:67], v[62:63]
	v_lshlrev_b32_e32 v66, 16, v36
	v_and_b32_e32 v67, 0xffff0000, v36
	v_lshlrev_b32_e32 v36, 16, v28
	v_mul_f32_e32 v25, 0xbfb8aa3b, v36
	v_exp_f32_e32 v25, v25
	v_mul_f32_e32 v28, 0xbfb8aa3b, v37
	v_exp_f32_e32 v31, v28
	v_and_b32_e32 v75, 0xffff0000, v43
	v_add_f32_e32 v25, 1.0, v25
	v_rcp_f32_e32 v72, v25
	v_add_f32_e32 v25, 1.0, v31
	v_rcp_f32_e32 v73, v25
	v_mul_f32_e32 v25, 0xbfb8aa3b, v74
	v_exp_f32_e32 v25, v25
	v_mul_f32_e32 v31, 0xbfb8aa3b, v75
	v_exp_f32_e32 v31, v31
	v_pk_mul_f32 v[36:37], v[72:73], v[36:37]
	v_add_f32_e32 v25, 1.0, v25
	v_rcp_f32_e32 v72, v25
	v_add_f32_e32 v25, 1.0, v31
	v_rcp_f32_e32 v73, v25
	s_waitcnt lgkmcnt(0)
	v_lshlrev_b32_e32 v76, 16, v47
	v_and_b32_e32 v77, 0xffff0000, v47
	v_and_b32_e32 v47, 0xffff0000, v42
	v_pk_mul_f32 v[72:73], v[72:73], v[74:75]
	v_lshlrev_b32_e32 v74, 16, v46
	v_and_b32_e32 v75, 0xffff0000, v46
	v_lshlrev_b32_e32 v46, 16, v42
	v_mul_f32_e32 v25, 0xbfb8aa3b, v46
	v_exp_f32_e32 v25, v25
	v_mul_f32_e32 v31, 0xbfb8aa3b, v47
	v_exp_f32_e32 v31, v31
	v_lshlrev_b32_e32 v84, 16, v41
	v_add_f32_e32 v25, 1.0, v25
	v_rcp_f32_e32 v80, v25
	v_add_f32_e32 v25, 1.0, v31
	v_rcp_f32_e32 v81, v25
	v_and_b32_e32 v85, 0xffff0000, v41
	v_mul_f32_e32 v25, 0xbfb8aa3b, v84
	v_exp_f32_e32 v25, v25
	v_mul_f32_e32 v31, 0xbfb8aa3b, v85
	v_exp_f32_e32 v31, v31
	v_lshlrev_b32_e32 v90, 16, v44
	v_add_f32_e32 v25, 1.0, v25
	v_and_b32_e32 v91, 0xffff0000, v44
	v_lshlrev_b32_e32 v82, 16, v45
	v_and_b32_e32 v83, 0xffff0000, v45
	v_rcp_f32_e32 v88, v25
	v_add_f32_e32 v25, 1.0, v31
	v_lshlrev_b32_e32 v44, 16, v40
	v_and_b32_e32 v45, 0xffff0000, v40
	v_pk_mul_f32 v[40:41], v[90:91], v[90:91]
	v_pk_mul_f32 v[86:87], v[82:83], v[82:83]
	v_rcp_f32_e32 v89, v25
	v_add_f32_e32 v25, v40, v41
	v_add_f32_e32 v25, v86, v25
	v_pk_mul_f32 v[42:43], v[74:75], v[74:75]
	v_add_f32_e32 v25, v87, v25
	v_add_f32_e32 v25, v42, v25
	v_pk_mul_f32 v[78:79], v[76:77], v[76:77]
	v_add_f32_e32 v25, v43, v25
	v_add_f32_e32 v25, v78, v25
	v_pk_mul_f32 v[28:29], v[66:67], v[66:67]
	v_add_f32_e32 v25, v79, v25
	v_add_f32_e32 v25, v28, v25
	v_pk_mul_f32 v[70:71], v[68:69], v[68:69]
	v_add_f32_e32 v25, v29, v25
	v_add_f32_e32 v25, v70, v25
	v_pk_mul_f32 v[50:51], v[48:49], v[48:49]
	v_and_b32_e32 v61, 0xffff0000, v39
	v_add_f32_e32 v25, v71, v25
	v_lshlrev_b32_e32 v33, 16, v39
	v_mov_b32_e32 v32, v61
	v_add_f32_e32 v25, v51, v25
	v_pk_mul_f32 v[64:65], v[32:33], v[32:33]
	v_add_f32_e32 v25, v50, v25
	v_add_f32_e32 v25, v65, v25
	v_add_f32_e32 v25, v64, v25
	ds_bpermute_b32 v28, v57, v25
	v_lshlrev_b32_e32 v50, 16, v30
	v_and_b32_e32 v51, 0xffff0000, v30
	v_mul_f32_e32 v29, 0xbfb8aa3b, v44
	v_mul_f32_e32 v31, 0xbfb8aa3b, v45
	s_waitcnt lgkmcnt(0)
	v_add_f32_e32 v25, v25, v28
	ds_bpermute_b32 v32, v58, v25
	v_mul_f32_e32 v30, 0xbfb8aa3b, v51
	v_exp_f32_e32 v29, v29
	v_exp_f32_e32 v31, v31
	v_exp_f32_e32 v34, v30
	s_waitcnt lgkmcnt(0)
	v_add_f32_e32 v25, v25, v32
	v_fmamk_f32 v25, v25, 0x3c800000, v24
	v_rsq_f32_e32 v32, v25
	v_mul_f32_e32 v25, 0xbfb8aa3b, v50
	v_exp_f32_e32 v25, v25
	v_pk_mul_f32 v[40:41], v[80:81], v[46:47]
	v_pk_mul_f32 v[46:47], v[32:33], v[66:67] op_sel_hi:[0,1]
	v_pk_mul_f32 v[46:47], v[10:11], v[46:47]
	v_add_f32_e32 v25, 1.0, v25
	v_pk_mul_f32 v[36:37], v[36:37], v[46:47]
	v_pk_mul_f32 v[46:47], v[32:33], v[68:69] op_sel_hi:[0,1]
	v_add_f32_e32 v28, 1.0, v29
	v_add_f32_e32 v29, 1.0, v31
	v_pk_mul_f32 v[30:31], v[12:13], v[46:47]
	v_rcp_f32_e32 v46, v25
	v_add_f32_e32 v25, 1.0, v34
	v_rcp_f32_e32 v28, v28
	v_rcp_f32_e32 v29, v29
	v_rcp_f32_e32 v47, v25
	v_mul_f32_e32 v25, 0xbfb8aa3b, v60
	v_exp_f32_e32 v25, v25
	v_pk_mul_f32 v[28:29], v[28:29], v[44:45]
	v_pk_mul_f32 v[44:45], v[32:33], v[90:91] op_sel_hi:[0,1]
	v_pk_mul_f32 v[44:45], v[2:3], v[44:45]
	v_add_f32_e32 v25, 1.0, v25
	v_pk_mul_f32 v[28:29], v[28:29], v[44:45]
	v_pk_mul_f32 v[44:45], v[32:33], v[82:83] op_sel_hi:[0,1]
	v_pk_mul_f32 v[62:63], v[62:63], v[30:31]
	v_pk_mul_f32 v[30:31], v[46:47], v[50:51]
	v_pk_mul_f32 v[46:47], v[32:33], v[48:49] op_sel_hi:[0,1]
	v_rcp_f32_e32 v48, v25
	v_pk_mul_f32 v[42:43], v[88:89], v[84:85]
	v_pk_mul_f32 v[44:45], v[4:5], v[44:45]
	v_pk_mul_f32 v[46:47], v[20:21], v[46:47]
	v_pk_mul_f32 v[42:43], v[42:43], v[44:45]
	v_pk_mul_f32 v[44:45], v[32:33], v[74:75] op_sel_hi:[0,1]
	v_pk_mul_f32 v[44:45], v[6:7], v[44:45]
	v_mov_b32_e32 v49, v32
	v_pk_mul_f32 v[40:41], v[40:41], v[44:45]
	v_pk_mul_f32 v[44:45], v[32:33], v[76:77] op_sel_hi:[0,1]
	v_pk_mul_f32 v[46:47], v[30:31], v[46:47] op_sel:[0,1] op_sel_hi:[1,0]
	v_mul_f32_e32 v30, v32, v33
	v_pk_mul_f32 v[32:33], v[48:49], v[60:61]
	v_pk_mul_f32 v[44:45], v[8:9], v[44:45]
	v_mov_b32_e32 v31, v33
	s_lshl_b64 s[20:21], s[10:11], 17
	v_pk_mul_f32 v[44:45], v[72:73], v[44:45]
	v_pk_mul_f32 v[30:31], v[16:17], v[30:31]
	v_mov_b32_e32 v39, v32
	v_pk_mul_f32 v[32:33], v[38:39], v[30:31]
	v_lshl_add_u64 v[48:49], v[14:15], 0, s[20:21]
	v_readlane_b32 s96, v247, 24
	v_cvt_pk_bf16_f32 v28, v28, v29
	v_cvt_pk_bf16_f32 v29, v42, v43
	v_cvt_pk_bf16_f32 v30, v40, v41
	v_cvt_pk_bf16_f32 v31, v44, v45
	v_cvt_pk_bf16_f32 v36, v36, v37
	v_cvt_pk_bf16_f32 v37, v62, v63
	v_cvt_pk_bf16_f32 v38, v46, v47
	v_cvt_pk_bf16_f32 v39, v32, v33
	global_store_dwordx4 v[48:49], v[28:31], off
	global_store_dwordx4 v[48:49], v[36:39], off offset:16
.Lld_wait:
	s_cmpk_eq_i32 s45, 0x80
	s_cbranch_scc1 .Lld_exit
	s_cmpk_gt_u32 s45, 0x7c
	s_cbranch_scc1 .Lld_w0
	s_and_b64 vcc, exec, s[8:9]
	s_cmp_lt_u32 s45, 2
	s_cbranch_scc1 .Lld_wearly
	s_cmp_lt_u32 s45, 4
	s_cbranch_scc1 .Lld_wplain
	s_cmpk_gt_u32 s45, 0x7a
	s_cbranch_scc1 .Lld_wplain
	s_cbranch_vccnz .Lld_w27
	s_waitcnt vmcnt(29)
	s_branch .Lld_bar
.Lld_w27:
	s_waitcnt vmcnt(27)
	s_branch .Lld_bar
.Lld_wplain:
	s_cbranch_vccnz .Lld_w22
	s_waitcnt vmcnt(24)
	s_branch .Lld_bar
